# K-loop SP1 load section: the 16 LDS fragment reads are issued before the SALU pointer math and DMA issue
# speedup vs baseline: 1.0026x; 1.0026x over previous
; #define PG8_STAGE(bufoff, gbase, voff) do { _Pragma("unroll") for (int _i = 0; _i < 2; ++_i) \
;         __builtin_amdgcn_global_load_lds((const unsigned*)((const char*)(gbase) + (voff)[_i]), (PG8_LAS unsigned*)(lds + (bufoff) + ldsw + _i * 8192), 16, 0, 0); } while (0)
; #define PG8_LDA(dst, b, h) do { _Pragma("unroll") for (int m = 0; m < 4; ++m) _Pragma("unroll") for (int k = 0; k < 2; ++k) dst[m][k] = *(const PG8_LAS bf16x8*)(lds + PG8_SA(b, h) + aoff + m * 2048 + k * 1024); } while (0)
; #define PG8_LDB(dst, b, h) do { _Pragma("unroll") for (int n = 0; n < 2; ++n) _Pragma("unroll") for (int k = 0; k < 2; ++k) dst[n][k] = *(const PG8_LAS bf16x8*)(lds + PG8_SB(b, h) + boff + n * 2048 + k * 1024); } while (0)
; #define PG8_MMA(ai, bj, At, Bt) do { __builtin_amdgcn_s_setprio(1); _Pragma("unroll") for (int m = 0; m < 4; ++m) _Pragma("unroll") for (int n = 0; n < 2; ++n) _Pragma("unroll") for (int k = 0; k < 2; ++k) \
;         acc[ai][bj][m][n] = __builtin_amdgcn_mfma_f32_16x16x32_bf16(Bt[n][k], At[m][k], acc[ai][bj][m][n], 0, 0, 0); __builtin_amdgcn_s_setprio(0); } while (0)
; #define PG8_WAIT_V(n) asm volatile("s_waitcnt vmcnt(" #n ")" ::: "memory")
; #define PG8_WAIT_L(n) asm volatile("s_waitcnt lgkmcnt(" #n ")" ::: "memory")
; #define PG8_BAR __builtin_amdgcn_s_barrier()
; #define PG8_SCHED __builtin_amdgcn_sched_barrier(0)
; template <class Epi, class Sched, bool ALIGN_EPI = false, bool SP2 = false>
; __device__ __forceinline__ void gemm_phase(PG8_LAS unsigned char* lds, const Gemm g, const Sched& S, const Epi& E) {
;     ...
;             PG8_LDB(B0, 0, 0); PG8_LDB(B1, 0, 1); PG8_SCHED; PG8_LDA(At, 0, 0); PG8_STAGE(PG8_SA(1, 1), a1 + hstep, voffA);
;             PG8_WAIT_V(8); PG8_WAIT_L(0); PG8_BAR; PG8_MMA(0, 0, At, B0); PG8_MMA(0, 1, At, B1); PG8_BAR; PG8_SCHED;
;             PG8_LDA(At, 0, 1); PG8_STAGE(PG8_SB(0, 0), b2, voffB); PG8_STAGE(PG8_SB(0, 1), b2 + hstep, voffB); PG8_STAGE(PG8_SA(0, 0), a2, voffA);
;             PG8_WAIT_V(8); PG8_WAIT_L(0); PG8_BAR; PG8_MMA(1, 0, At, B0); PG8_MMA(1, 1, At, B1); PG8_BAR; PG8_SCHED;
.LBB0_56:
	s_add_i32 s65, 0, 0x10000
	v_add_u32_e32 v0, s65, v188
	ds_read_b128 v[132:135], v0
	ds_read_b128 v[136:139], v0 offset:1024
	ds_read_b128 v[140:143], v0 offset:2048
	ds_read_b128 v[144:147], v0 offset:3072
	v_add_u32_e32 v0, 0x14000, v188
	ds_read_b128 v[148:151], v0
	ds_read_b128 v[152:155], v0 offset:1024
	ds_read_b128 v[156:159], v0 offset:2048
	ds_read_b128 v[160:163], v0 offset:3072
	ds_read_b128 v[164:167], v235
	ds_read_b128 v[168:171], v235 offset:1024
	ds_read_b128 v[172:175], v235 offset:2048
	ds_read_b128 v[176:179], v235 offset:3072
	ds_read_b128 v[180:183], v235 offset:4096
	ds_read_b128 v[184:187], v235 offset:5120
	ds_read_b128 v[236:239], v235 offset:6144
	ds_read_b128 v[240:243], v235 offset:7168
	s_add_i32 s2, s34, 2
	s_add_u32 s35, s28, s30
	s_addc_u32 s62, s29, s31
	s_add_u32 s63, s35, 0x100
	s_addc_u32 s35, s62, 0
	s_add_u32 s62, s60, s30
	s_addc_u32 s64, s61, s31
	s_cmp_eq_u32 s48, s34
	s_cselect_b32 s35, s1, s35
	s_cselect_b32 s34, s0, s63
	s_cselect_b32 s63, s27, s64
	s_cselect_b32 s62, s26, s62
	s_add_i32 s64, 0, 0x14000
	v_lshl_add_u64 v[2:3], v[204:205], 0, s[30:31]
	s_add_i32 m0, s43, 0xc000
	s_nop 0
	global_load_lds_dwordx4 v[2:3], off
	v_lshl_add_u64 v[2:3], v[206:207], 0, s[30:31]
	s_add_i32 m0, s43, 0xe000
	s_nop 0
	global_load_lds_dwordx4 v[2:3], off
	s_waitcnt vmcnt(8)
	s_waitcnt lgkmcnt(0)
	s_setprio 1
	s_barrier
	v_mfma_f32_16x16x32_bf16 v[116:119], v[132:135], v[164:167], v[116:119]
	v_mfma_f32_16x16x32_bf16 v[116:119], v[136:139], v[168:171], v[116:119]
	v_mfma_f32_16x16x32_bf16 v[120:123], v[140:143], v[164:167], v[120:123]
	v_mfma_f32_16x16x32_bf16 v[120:123], v[144:147], v[168:171], v[120:123]
	v_mfma_f32_16x16x32_bf16 v[104:107], v[140:143], v[172:175], v[104:107]
	v_mfma_f32_16x16x32_bf16 v[104:107], v[144:147], v[176:179], v[104:107]
	v_mfma_f32_16x16x32_bf16 v[100:103], v[132:135], v[172:175], v[100:103]
	v_mfma_f32_16x16x32_bf16 v[100:103], v[136:139], v[176:179], v[100:103]
	v_mfma_f32_16x16x32_bf16 v[76:79], v[132:135], v[180:183], v[76:79]
	v_mfma_f32_16x16x32_bf16 v[76:79], v[136:139], v[184:187], v[76:79]
	v_mfma_f32_16x16x32_bf16 v[80:83], v[140:143], v[180:183], v[80:83]
	v_mfma_f32_16x16x32_bf16 v[80:83], v[144:147], v[184:187], v[80:83]
	v_mfma_f32_16x16x32_bf16 v[48:51], v[140:143], v[236:239], v[48:51]
	v_mfma_f32_16x16x32_bf16 v[48:51], v[144:147], v[240:243], v[48:51]
	v_mfma_f32_16x16x32_bf16 v[44:47], v[132:135], v[236:239], v[44:47]
	v_mfma_f32_16x16x32_bf16 v[44:47], v[136:139], v[240:243], v[44:47]
	v_mfma_f32_16x16x32_bf16 v[124:127], v[148:151], v[164:167], v[124:127]
	v_mfma_f32_16x16x32_bf16 v[124:127], v[152:155], v[168:171], v[124:127]
	v_mfma_f32_16x16x32_bf16 v[128:131], v[156:159], v[164:167], v[128:131]
	v_mfma_f32_16x16x32_bf16 v[128:131], v[160:163], v[168:171], v[128:131]
	v_mfma_f32_16x16x32_bf16 v[112:115], v[156:159], v[172:175], v[112:115]
	v_mfma_f32_16x16x32_bf16 v[112:115], v[160:163], v[176:179], v[112:115]
	v_mfma_f32_16x16x32_bf16 v[108:111], v[148:151], v[172:175], v[108:111]
	v_mfma_f32_16x16x32_bf16 v[108:111], v[152:155], v[176:179], v[108:111]
	v_mfma_f32_16x16x32_bf16 v[92:95], v[148:151], v[180:183], v[92:95]
	v_mfma_f32_16x16x32_bf16 v[92:95], v[152:155], v[184:187], v[92:95]
	v_mfma_f32_16x16x32_bf16 v[96:99], v[156:159], v[180:183], v[96:99]
	v_mfma_f32_16x16x32_bf16 v[96:99], v[160:163], v[184:187], v[96:99]
	v_mfma_f32_16x16x32_bf16 v[72:75], v[156:159], v[236:239], v[72:75]
	v_mfma_f32_16x16x32_bf16 v[72:75], v[160:163], v[240:243], v[72:75]
	v_mfma_f32_16x16x32_bf16 v[68:71], v[148:151], v[236:239], v[68:71]
	v_mfma_f32_16x16x32_bf16 v[68:71], v[152:155], v[240:243], v[68:71]
	s_barrier
	s_setprio 0
	s_add_i32 s65, s65, s41
	v_lshl_add_u64 v[208:209], s[62:63], 0, v[192:193]
	s_mov_b32 m0, s65
	ds_read_b128 v[164:167], v235 offset:16384
	ds_read_b128 v[168:171], v235 offset:17408
	ds_read_b128 v[172:175], v235 offset:18432
	ds_read_b128 v[176:179], v235 offset:19456
	ds_read_b128 v[180:183], v235 offset:20480
	ds_read_b128 v[184:187], v235 offset:21504
	ds_read_b128 v[236:239], v235 offset:22528
	ds_read_b128 v[240:243], v235 offset:23552
	global_load_lds_dwordx4 v[208:209], off
	s_add_i32 m0, s65, 0x2000
	v_lshl_add_u64 v[244:245], s[62:63], 0, v[196:197]
	s_add_u32 s62, s62, s16
	s_addc_u32 s63, s63, 0
	s_add_i32 s64, s64, s41
	global_load_lds_dwordx4 v[244:245], off
	v_lshl_add_u64 v[246:247], s[62:63], 0, v[192:193]
	s_mov_b32 m0, s64
	v_lshl_add_u64 v[248:249], s[62:63], 0, v[196:197]
	global_load_lds_dwordx4 v[246:247], off
	s_add_i32 m0, s64, 0x2000
	v_lshl_add_u64 v[250:251], s[34:35], 0, v[190:191]
	global_load_lds_dwordx4 v[248:249], off
	s_mov_b32 m0, s43
	v_lshl_add_u64 v[212:213], s[34:35], 0, v[194:195]
	global_load_lds_dwordx4 v[250:251], off
	s_mov_b32 m0, s44
	s_nop 0
	global_load_lds_dwordx4 v[212:213], off
	s_waitcnt vmcnt(8)
	s_waitcnt lgkmcnt(0)
	s_setprio 1
	s_barrier
; #define PG8_STAGE(bufoff, gbase, voff) do { _Pragma("unroll") for (int _i = 0; _i < 2; ++_i) \
;         __builtin_amdgcn_global_load_lds((const unsigned*)((const char*)(gbase) + (voff)[_i]), (PG8_LAS unsigned*)(lds + (bufoff) + ldsw + _i * 8192), 16, 0, 0); } while (0)
; #define PG8_LDA(dst, b, h) do { _Pragma("unroll") for (int m = 0; m < 4; ++m) _Pragma("unroll") for (int k = 0; k < 2; ++k) dst[m][k] = *(const PG8_LAS bf16x8*)(lds + PG8_SA(b, h) + aoff + m * 2048 + k * 1024); } while (0)
; #define PG8_LDB(dst, b, h) do { _Pragma("unroll") for (int n = 0; n < 2; ++n) _Pragma("unroll") for (int k = 0; k < 2; ++k) dst[n][k] = *(const PG8_LAS bf16x8*)(lds + PG8_SB(b, h) + boff + n * 2048 + k * 1024); } while (0)
; #define PG8_MMA(ai, bj, At, Bt) do { __builtin_amdgcn_s_setprio(1); _Pragma("unroll") for (int m = 0; m < 4; ++m) _Pragma("unroll") for (int n = 0; n < 2; ++n) _Pragma("unroll") for (int k = 0; k < 2; ++k) \
;         acc[ai][bj][m][n] = __builtin_amdgcn_mfma_f32_16x16x32_bf16(Bt[n][k], At[m][k], acc[ai][bj][m][n], 0, 0, 0); __builtin_amdgcn_s_setprio(0); } while (0)
; #define PG8_WAIT_V(n) asm volatile("s_waitcnt vmcnt(" #n ")" ::: "memory")
; #define PG8_WAIT_L(n) asm volatile("s_waitcnt lgkmcnt(" #n ")" ::: "memory")
; #define PG8_BAR __builtin_amdgcn_s_barrier()
; #define PG8_SCHED __builtin_amdgcn_sched_barrier(0)
; template <class Epi, class Sched, bool ALIGN_EPI = false, bool SP2 = false>
; __device__ __forceinline__ void gemm_phase(PG8_LAS unsigned char* lds, const Gemm g, const Sched& S, const Epi& E) {
;     ...
;             PG8_WAIT_V(8); PG8_WAIT_L(0); PG8_BAR; PG8_MMA(1, 0, At, B0); PG8_MMA(1, 1, At, B1); PG8_BAR; PG8_SCHED;
;             PG8_LDB(B0, 1, 0); PG8_LDB(B1, 1, 1); PG8_SCHED; PG8_LDA(At, 1, 0); PG8_STAGE(PG8_SA(0, 1), a2 + hstep, voffA);
;             PG8_WAIT_V(8); PG8_WAIT_L(0); PG8_BAR; PG8_MMA(0, 0, At, B0); PG8_MMA(0, 1, At, B1); PG8_BAR; PG8_SCHED;
	v_mfma_f32_16x16x32_bf16 v[60:63], v[132:135], v[164:167], v[60:63]
	v_mfma_f32_16x16x32_bf16 v[60:63], v[136:139], v[168:171], v[60:63]
	v_mfma_f32_16x16x32_bf16 v[64:67], v[140:143], v[164:167], v[64:67]
	v_mfma_f32_16x16x32_bf16 v[64:67], v[144:147], v[168:171], v[64:67]
	v_mfma_f32_16x16x32_bf16 v[40:43], v[140:143], v[172:175], v[40:43]
	v_mfma_f32_16x16x32_bf16 v[40:43], v[144:147], v[176:179], v[40:43]
	v_mfma_f32_16x16x32_bf16 v[36:39], v[132:135], v[172:175], v[36:39]
	v_mfma_f32_16x16x32_bf16 v[36:39], v[136:139], v[176:179], v[36:39]
	v_mfma_f32_16x16x32_bf16 v[20:23], v[132:135], v[180:183], v[20:23]
	v_mfma_f32_16x16x32_bf16 v[20:23], v[136:139], v[184:187], v[20:23]
	v_mfma_f32_16x16x32_bf16 v[24:27], v[140:143], v[180:183], v[24:27]
	v_mfma_f32_16x16x32_bf16 v[24:27], v[144:147], v[184:187], v[24:27]
	v_mfma_f32_16x16x32_bf16 v[2:5], v[132:135], v[236:239], v[4:7]
	v_mfma_f32_16x16x32_bf16 v[2:5], v[136:139], v[240:243], v[2:5]
	v_mfma_f32_16x16x32_bf16 v[6:9], v[140:143], v[236:239], v[8:11]
	v_mfma_f32_16x16x32_bf16 v[8:11], v[144:147], v[240:243], v[6:9]
	v_mfma_f32_16x16x32_bf16 v[84:87], v[148:151], v[164:167], v[84:87]
	v_mfma_f32_16x16x32_bf16 v[84:87], v[152:155], v[168:171], v[84:87]
	v_mfma_f32_16x16x32_bf16 v[88:91], v[156:159], v[164:167], v[88:91]
	v_mfma_f32_16x16x32_bf16 v[88:91], v[160:163], v[168:171], v[88:91]
	v_mfma_f32_16x16x32_bf16 v[56:59], v[156:159], v[172:175], v[56:59]
	v_mfma_f32_16x16x32_bf16 v[56:59], v[160:163], v[176:179], v[56:59]
	v_mfma_f32_16x16x32_bf16 v[52:55], v[148:151], v[172:175], v[52:55]
	v_mfma_f32_16x16x32_bf16 v[52:55], v[152:155], v[176:179], v[52:55]
	v_mfma_f32_16x16x32_bf16 v[28:31], v[148:151], v[180:183], v[28:31]
	v_mfma_f32_16x16x32_bf16 v[28:31], v[152:155], v[184:187], v[28:31]
	v_mfma_f32_16x16x32_bf16 v[32:35], v[156:159], v[180:183], v[32:35]
	v_mfma_f32_16x16x32_bf16 v[32:35], v[160:163], v[184:187], v[32:35]
	v_mfma_f32_16x16x32_bf16 v[16:19], v[156:159], v[236:239], v[16:19]
	v_mfma_f32_16x16x32_bf16 v[16:19], v[160:163], v[240:243], v[16:19]
	v_mfma_f32_16x16x32_bf16 v[12:15], v[148:151], v[236:239], v[12:15]
	v_mfma_f32_16x16x32_bf16 v[12:15], v[152:155], v[240:243], v[12:15]
	s_barrier
	s_setprio 0
	s_add_i32 s62, 0, 0x18000
	v_add_u32_e32 v0, s62, v188
	s_add_i32 s63, 0, 0x1c000
	ds_read_b128 v[132:135], v0
	ds_read_b128 v[136:139], v0 offset:1024
	ds_read_b128 v[140:143], v0 offset:2048
	ds_read_b128 v[144:147], v0 offset:3072
	v_add_u32_e32 v0, s63, v188
	ds_read_b128 v[148:151], v0
	ds_read_b128 v[152:155], v0 offset:1024
	ds_read_b128 v[156:159], v0 offset:2048
	ds_read_b128 v[160:163], v0 offset:3072
	s_add_u32 s34, s34, s16
	s_addc_u32 s35, s35, 0
	s_mov_b32 m0, s45
	v_lshl_add_u64 v[6:7], s[34:35], 0, v[190:191]
	ds_read_b128 v[164:167], v235 offset:32768
	ds_read_b128 v[168:171], v235 offset:33792
	ds_read_b128 v[172:175], v235 offset:34816
	ds_read_b128 v[176:179], v235 offset:35840
	ds_read_b128 v[180:183], v235 offset:36864
	ds_read_b128 v[184:187], v235 offset:37888
	ds_read_b128 v[236:239], v235 offset:38912
	ds_read_b128 v[240:243], v235 offset:39936
	global_load_lds_dwordx4 v[6:7], off
	v_lshl_add_u64 v[6:7], s[34:35], 0, v[194:195]
	s_mov_b32 m0, s46
	s_nop 0
	global_load_lds_dwordx4 v[6:7], off
	s_waitcnt vmcnt(8)
	s_waitcnt lgkmcnt(0)
	s_setprio 1
	s_barrier
	v_mfma_f32_16x16x32_bf16 v[116:119], v[132:135], v[164:167], v[116:119]
	v_mfma_f32_16x16x32_bf16 v[116:119], v[136:139], v[168:171], v[116:119]
	v_mfma_f32_16x16x32_bf16 v[120:123], v[140:143], v[164:167], v[120:123]
	v_mfma_f32_16x16x32_bf16 v[120:123], v[144:147], v[168:171], v[120:123]
	v_mfma_f32_16x16x32_bf16 v[104:107], v[140:143], v[172:175], v[104:107]
	v_mfma_f32_16x16x32_bf16 v[104:107], v[144:147], v[176:179], v[104:107]
	v_mfma_f32_16x16x32_bf16 v[100:103], v[132:135], v[172:175], v[100:103]
	v_mfma_f32_16x16x32_bf16 v[100:103], v[136:139], v[176:179], v[100:103]
	v_mfma_f32_16x16x32_bf16 v[76:79], v[132:135], v[180:183], v[76:79]
	v_mfma_f32_16x16x32_bf16 v[76:79], v[136:139], v[184:187], v[76:79]
	v_mfma_f32_16x16x32_bf16 v[80:83], v[140:143], v[180:183], v[80:83]
	v_mfma_f32_16x16x32_bf16 v[80:83], v[144:147], v[184:187], v[80:83]
	v_mfma_f32_16x16x32_bf16 v[48:51], v[140:143], v[236:239], v[48:51]
	v_mfma_f32_16x16x32_bf16 v[48:51], v[144:147], v[240:243], v[48:51]
	v_mfma_f32_16x16x32_bf16 v[44:47], v[132:135], v[236:239], v[44:47]
	v_mfma_f32_16x16x32_bf16 v[44:47], v[136:139], v[240:243], v[44:47]
	v_mfma_f32_16x16x32_bf16 v[124:127], v[148:151], v[164:167], v[124:127]
	v_mfma_f32_16x16x32_bf16 v[124:127], v[152:155], v[168:171], v[124:127]
	v_mfma_f32_16x16x32_bf16 v[128:131], v[156:159], v[164:167], v[128:131]
	v_mfma_f32_16x16x32_bf16 v[128:131], v[160:163], v[168:171], v[128:131]
	v_mfma_f32_16x16x32_bf16 v[112:115], v[156:159], v[172:175], v[112:115]
	v_mfma_f32_16x16x32_bf16 v[112:115], v[160:163], v[176:179], v[112:115]
	v_mfma_f32_16x16x32_bf16 v[108:111], v[148:151], v[172:175], v[108:111]
	v_mfma_f32_16x16x32_bf16 v[108:111], v[152:155], v[176:179], v[108:111]
	v_mfma_f32_16x16x32_bf16 v[92:95], v[148:151], v[180:183], v[92:95]
	v_mfma_f32_16x16x32_bf16 v[92:95], v[152:155], v[184:187], v[92:95]
	v_mfma_f32_16x16x32_bf16 v[96:99], v[156:159], v[180:183], v[96:99]
	v_mfma_f32_16x16x32_bf16 v[96:99], v[160:163], v[184:187], v[96:99]
	v_mfma_f32_16x16x32_bf16 v[72:75], v[156:159], v[236:239], v[72:75]
	v_mfma_f32_16x16x32_bf16 v[72:75], v[160:163], v[240:243], v[72:75]
	v_mfma_f32_16x16x32_bf16 v[68:71], v[148:151], v[236:239], v[68:71]
	v_mfma_f32_16x16x32_bf16 v[68:71], v[152:155], v[240:243], v[68:71]
	s_barrier
; #define PG8_STAGE(bufoff, gbase, voff) do { _Pragma("unroll") for (int _i = 0; _i < 2; ++_i) \
;         __builtin_amdgcn_global_load_lds((const unsigned*)((const char*)(gbase) + (voff)[_i]), (PG8_LAS unsigned*)(lds + (bufoff) + ldsw + _i * 8192), 16, 0, 0); } while (0)
; #define PG8_LDA(dst, b, h) do { _Pragma("unroll") for (int m = 0; m < 4; ++m) _Pragma("unroll") for (int k = 0; k < 2; ++k) dst[m][k] = *(const PG8_LAS bf16x8*)(lds + PG8_SA(b, h) + aoff + m * 2048 + k * 1024); } while (0)
; #define PG8_MMA(ai, bj, At, Bt) do { __builtin_amdgcn_s_setprio(1); _Pragma("unroll") for (int m = 0; m < 4; ++m) _Pragma("unroll") for (int n = 0; n < 2; ++n) _Pragma("unroll") for (int k = 0; k < 2; ++k) \
;         acc[ai][bj][m][n] = __builtin_amdgcn_mfma_f32_16x16x32_bf16(Bt[n][k], At[m][k], acc[ai][bj][m][n], 0, 0, 0); __builtin_amdgcn_s_setprio(0); } while (0)
; #define PG8_WAIT_V(n) asm volatile("s_waitcnt vmcnt(" #n ")" ::: "memory")
; #define PG8_WAIT_L(n) asm volatile("s_waitcnt lgkmcnt(" #n ")" ::: "memory")
; #define PG8_BAR __builtin_amdgcn_s_barrier()
; #define PG8_SCHED __builtin_amdgcn_sched_barrier(0)
; template <class Epi, class Sched, bool ALIGN_EPI = false, bool SP2 = false>
; __device__ __forceinline__ void gemm_phase(PG8_LAS unsigned char* lds, const Gemm g, const Sched& S, const Epi& E) {
;     ...
;         for (int t = 0; t < nt; t += 2) {
;     ...
;             PG8_LDA(At, 1, 1); PG8_STAGE(PG8_SB(1, 0), b3, voffB); PG8_STAGE(PG8_SB(1, 1), b3 + hstep, voffB); PG8_STAGE(PG8_SA(1, 0), a3, voffA);
;             PG8_WAIT_V(8); PG8_WAIT_L(0); PG8_BAR; PG8_MMA(1, 0, At, B0); PG8_MMA(1, 1, At, B1); PG8_BAR; PG8_SCHED;
	s_setprio 0
	s_add_i32 s34, s62, s41
	v_lshl_add_u64 v[6:7], v[208:209], 0, s[92:93]
	s_mov_b32 m0, s34
	ds_read_b128 v[164:167], v235 offset:49152
	ds_read_b128 v[168:171], v235 offset:50176
	ds_read_b128 v[172:175], v235 offset:51200
	ds_read_b128 v[176:179], v235 offset:52224
	ds_read_b128 v[180:183], v235 offset:53248
	ds_read_b128 v[184:187], v235 offset:54272
	ds_read_b128 v[236:239], v235 offset:55296
	ds_read_b128 v[240:243], v235 offset:56320
	global_load_lds_dwordx4 v[6:7], off
	v_lshl_add_u64 v[6:7], v[244:245], 0, s[92:93]
	s_add_i32 m0, s34, 0x2000
	s_add_i32 s34, s63, s41
	global_load_lds_dwordx4 v[6:7], off
	v_lshl_add_u64 v[6:7], v[246:247], 0, s[92:93]
	s_mov_b32 m0, s34
	s_nop 0
	global_load_lds_dwordx4 v[6:7], off
	v_lshl_add_u64 v[6:7], v[248:249], 0, s[92:93]
	s_add_i32 m0, s34, 0x2000
	s_nop 0
	global_load_lds_dwordx4 v[6:7], off
	v_lshl_add_u64 v[6:7], v[250:251], 0, s[92:93]
	s_mov_b32 m0, s51
	s_nop 0
	global_load_lds_dwordx4 v[6:7], off
	v_lshl_add_u64 v[6:7], v[212:213], 0, s[92:93]
	s_mov_b32 m0, s52
	s_nop 0
	global_load_lds_dwordx4 v[6:7], off
	s_waitcnt vmcnt(8)
	s_waitcnt lgkmcnt(0)
	s_setprio 1
	s_barrier
	v_mfma_f32_16x16x32_bf16 v[60:63], v[132:135], v[164:167], v[60:63]
	v_mfma_f32_16x16x32_bf16 v[60:63], v[136:139], v[168:171], v[60:63]
	v_mfma_f32_16x16x32_bf16 v[64:67], v[140:143], v[164:167], v[64:67]
	v_mfma_f32_16x16x32_bf16 v[64:67], v[144:147], v[168:171], v[64:67]
	v_mfma_f32_16x16x32_bf16 v[40:43], v[140:143], v[172:175], v[40:43]
	v_mfma_f32_16x16x32_bf16 v[40:43], v[144:147], v[176:179], v[40:43]
	v_mfma_f32_16x16x32_bf16 v[36:39], v[132:135], v[172:175], v[36:39]
	v_mfma_f32_16x16x32_bf16 v[36:39], v[136:139], v[176:179], v[36:39]
	v_mfma_f32_16x16x32_bf16 v[20:23], v[132:135], v[180:183], v[20:23]
	v_mfma_f32_16x16x32_bf16 v[20:23], v[136:139], v[184:187], v[20:23]
	v_mfma_f32_16x16x32_bf16 v[24:27], v[140:143], v[180:183], v[24:27]
	v_mfma_f32_16x16x32_bf16 v[24:27], v[144:147], v[184:187], v[24:27]
	v_mfma_f32_16x16x32_bf16 v[8:11], v[140:143], v[236:239], v[8:11]
	v_mfma_f32_16x16x32_bf16 v[8:11], v[144:147], v[240:243], v[8:11]
	v_mfma_f32_16x16x32_bf16 v[2:5], v[132:135], v[236:239], v[2:5]
	v_mfma_f32_16x16x32_bf16 v[4:7], v[136:139], v[240:243], v[2:5]
	v_mfma_f32_16x16x32_bf16 v[84:87], v[148:151], v[164:167], v[84:87]
	v_mfma_f32_16x16x32_bf16 v[84:87], v[152:155], v[168:171], v[84:87]
	v_mfma_f32_16x16x32_bf16 v[88:91], v[156:159], v[164:167], v[88:91]
	v_mfma_f32_16x16x32_bf16 v[88:91], v[160:163], v[168:171], v[88:91]
	v_mfma_f32_16x16x32_bf16 v[56:59], v[156:159], v[172:175], v[56:59]
	v_mfma_f32_16x16x32_bf16 v[56:59], v[160:163], v[176:179], v[56:59]
	v_mfma_f32_16x16x32_bf16 v[52:55], v[148:151], v[172:175], v[52:55]
	v_mfma_f32_16x16x32_bf16 v[52:55], v[152:155], v[176:179], v[52:55]
	v_mfma_f32_16x16x32_bf16 v[28:31], v[148:151], v[180:183], v[28:31]
	v_mfma_f32_16x16x32_bf16 v[28:31], v[152:155], v[184:187], v[28:31]
	v_mfma_f32_16x16x32_bf16 v[32:35], v[156:159], v[180:183], v[32:35]
	v_mfma_f32_16x16x32_bf16 v[32:35], v[160:163], v[184:187], v[32:35]
	v_mfma_f32_16x16x32_bf16 v[16:19], v[156:159], v[236:239], v[16:19]
	v_mfma_f32_16x16x32_bf16 v[16:19], v[160:163], v[240:243], v[16:19]
	v_mfma_f32_16x16x32_bf16 v[12:15], v[148:151], v[236:239], v[12:15]
	v_mfma_f32_16x16x32_bf16 v[12:15], v[152:155], v[240:243], v[12:15]
	s_barrier
	s_setprio 0
	s_add_u32 s30, s30, 0x100
	s_addc_u32 s31, s31, 0
	s_cmp_ge_u32 s2, s47
	s_cbranch_scc1 .LBB0_58
	s_mov_b32 s34, s2
	s_branch .LBB0_54
